# weight-conversion phase: wave index rotated between job groups so small jobs land on waves idle in the FFN jobs
# speedup vs baseline: 1.0137x; 1.0053x over previous
; #define TRJOB(W_, K_, ld_, col0_, ncols_, WT_, pitch_, koff_, rowoff_, mode_, ks_, ns_) do { const int nblk_ = (ncols_) / 32, nit_ = ((K_) / 64) * nblk_; \
;     for (int it = gw; it < nit_; it += NGW) tr_item(W_, ld_, col0_, WT_, pitch_, koff_, rowoff_, mode_, ks_, ns_, nblk_, it, scr, lane); } while (0)
; DI void phase_convert(ArgsP a, int tb_, int l, char* shm, int vcu, int G) {
;     ...
;     const float* wi = a->in[I_WIN] + (size_t)l * D * DIN;
;     TRJOB(wi, D, DIN, 0, 416, win, D, 0, 0, 0, nullptr, nullptr);
.LBB0_58:
	s_or_b64 exec, exec, s[4:5]
	s_cmpk_eq_u32 s37, 0x800
	s_cselect_b32 s0, 0x180, 0
	v_add_u32_e32 v55, s0, v55
	v_cmp_le_u32_e32 vcc, s37, v55
	v_subrev_u32_e32 v56, s37, v55
	s_nop 1
	v_cndmask_b32_e32 v55, v55, v56, vcc
	v_lshlrev_b32_e32 v56, 5, v55
	v_readlane_b32 s4, v255, 19
	v_readlane_b32 s5, v255, 20
	s_xor_b64 s[4:5], s[4:5], -1
	v_writelane_b32 v255, s4, 23
	s_waitcnt lgkmcnt(0)
	s_add_u32 s14, s12, 0x6f00000
	s_mul_i32 s2, s26, 0x15c0000
	v_writelane_b32 v255, s5, 24
	s_load_dwordx2 s[4:5], s[10:11], 0x58
	s_addc_u32 s15, s13, 0
	s_movk_i32 s0, 0xd0
	v_cmp_gt_i32_e32 vcc, s0, v55
	s_waitcnt lgkmcnt(0)
	s_add_u32 s6, s4, s2
	s_addc_u32 s7, s5, 0
	s_and_saveexec_b64 s[4:5], vcc
	s_cbranch_execz .LBB0_61
	v_lshrrev_b32_e32 v29, 3, v39
	v_mov_b32_e32 v43, v189
	v_add_u32_e32 v0, v57, v42
	v_mul_u32_u24_e32 v1, 0x84, v29
	v_mul_u32_u24_e32 v2, 0x420, v37
	v_lshlrev_b32_e32 v3, 2, v29
	v_lshl_add_u64 v[24:25], s[6:7], 0, v[42:43]
	v_lshl_add_u64 v[26:27], s[14:15], 0, v[42:43]
	v_add3_u32 v35, v57, v2, v3
	v_lshlrev_b32_e32 v28, 5, v55
	s_lshl_b32 s2, s37, 5
	s_mov_b64 s[8:9], 0
	v_add_u32_e32 v41, v0, v1
	v_mov_b32_e32 v43, v55

; #define TRJOB(W_, K_, ld_, col0_, ncols_, WT_, pitch_, koff_, rowoff_, mode_, ks_, ns_) do { const int nblk_ = (ncols_) / 32, nit_ = ((K_) / 64) * nblk_; \
;     for (int it = gw; it < nit_; it += NGW) tr_item(W_, ld_, col0_, WT_, pitch_, koff_, rowoff_, mode_, ks_, ns_, nblk_, it, scr, lane); } while (0)
; DI void phase_convert(ArgsP a, int tb_, int l, char* shm, int vcu, int G) {
;     ...
;     TRJOB(wi, D, DIN, 1952, 32, win, D, 0, 2560, 0, nullptr, nullptr);
.LBB0_67:
	s_or_b64 exec, exec, s[8:9]
	v_cmp_gt_i32_e32 vcc, 16, v55
	s_and_saveexec_b64 s[8:9], vcc
	s_cbranch_execz .LBB0_70
	v_mov_b32_e32 v43, v189
	v_lshrrev_b32_e32 v18, 3, v39
	v_lshl_add_u64 v[0:1], s[6:7], 0, v[42:43]
	s_mov_b64 s[16:17], 0x1e80
	v_lshl_add_u64 v[12:13], v[0:1], 0, s[16:17]
	v_lshl_add_u64 v[0:1], s[14:15], 0, v[42:43]
	v_lshlrev_b32_e32 v188, 11, v18
	v_add_u32_e32 v2, v57, v42
	v_mul_u32_u24_e32 v3, 0x84, v18
	v_mul_u32_u24_e32 v4, 0x420, v37
	v_lshlrev_b32_e32 v5, 2, v18
	v_lshl_add_u64 v[14:15], v[0:1], 0, v[188:189]
	v_lshlrev_b32_e32 v0, 6, v34
	v_add3_u32 v19, v57, v4, v5
	v_lshlrev_b32_e32 v16, 6, v55
	s_lshl_b32 s2, s35, 9
	s_mov_b64 s[16:17], 0
	v_add_u32_e32 v20, v2, v3
	v_mov_b32_e32 v21, v55

; #define TRJOB(W_, K_, ld_, col0_, ncols_, WT_, pitch_, koff_, rowoff_, mode_, ks_, ns_) do { const int nblk_ = (ncols_) / 32, nit_ = ((K_) / 64) * nblk_; \
;     for (int it = gw; it < nit_; it += NGW) tr_item(W_, ld_, col0_, WT_, pitch_, koff_, rowoff_, mode_, ks_, ns_, nblk_, it, scr, lane); } while (0)
; DI void phase_convert(ArgsP a, int tb_, int l, char* shm, int vcu, int G) {
;     ...
;     TRJOB(a->in[I_WUQ] + (size_t)l * 256 * 768, 256, 768, 0, 768, wuq, 256, 0, 0, 0, a->in[I_GCQ] + l * 256, nullptr);
;     TRJOB(a->in[I_WUKV] + (size_t)l * 128 * 1024, 128, 1024, 0, 1024, wukv, 256, 0, 0, 0, a->in[I_GCKV] + l * 128, nullptr);
.LBB0_92:
	s_or_b64 exec, exec, s[8:9]
	s_cmpk_eq_u32 s37, 0x800
	s_cselect_b32 s0, 0x100, 0
	v_add_u32_e32 v55, s0, v55
	v_cmp_le_u32_e32 vcc, s37, v55
	v_subrev_u32_e32 v56, s37, v55
	s_nop 1
	v_cndmask_b32_e32 v55, v55, v56, vcc
	v_lshlrev_b32_e32 v56, 5, v55
	v_cmp_gt_i32_e64 s[4:5], s96, v55
	s_add_u32 s16, s12, 0x7ae0000
	s_addc_u32 s17, s13, 0
	v_cmp_lt_i32_e32 vcc, 63, v55
	s_and_saveexec_b64 s[6:7], vcc
	s_xor_b64 s[6:7], exec, s[6:7]
	s_cbranch_execz .LBB0_95
	v_lshrrev_b32_e32 v36, 3, v39
	s_movk_i32 s0, 0x84
	v_mov_b32_e32 v0, 0x420
	v_mad_u32_u24 v59, v36, s0, v0
	v_mov_b32_e32 v0, 0x840
	v_lshlrev_b32_e32 v188, 2, v37
	v_mad_u32_u24 v61, v36, s0, v0
	v_mov_b32_e32 v0, 0xc60
	v_mul_u32_u24_e32 v52, 0x84, v36
	v_or_b32_e32 v53, 8, v36
	v_or_b32_e32 v60, 16, v36
	v_or_b32_e32 v62, 24, v36
	v_mad_u32_u24 v63, v36, s0, v0
	v_mul_u32_u24_e32 v58, 0x420, v37
	v_mov_b32_e32 v41, v189
	v_mov_b64_e32 v[38:39], v[188:189]
